# prompt sliding-window attention items moved from phase 3 (all workgroups) into phase 4's non-scan workgroups 128..255 (4 items each), which were idle while the GDN scan runs
# speedup vs baseline: 1.0061x; 1.0025x over previous
_Z10hybrid_fwd6Params:
	s_load_dwordx4 s[76:79], s[0:1], 0xd8
	s_load_dword s33, s[0:1], 0xe8
	s_add_u32 s4, s0, 0xe8
	s_addc_u32 s5, s1, 0
	v_writelane_b32 v255, s4, 0
	s_waitcnt lgkmcnt(0)
	s_sub_i32 s3, s79, s78
	v_writelane_b32 v255, s5, 1
	s_cmp_lt_i32 s3, 2
	s_mov_b32 s3, 0
	s_cselect_b64 s[4:5], -1, 0
	v_writelane_b32 v255, s3, 2
	v_writelane_b32 v255, s3, 41
	v_writelane_b32 v255, s4, 3
	s_and_b64 vcc, exec, s[4:5]
	s_nop 0
	v_writelane_b32 v255, s5, 4
	s_cbranch_vccnz .LBB0_8
	v_and_b32_e32 v1, 0x3ff, v0
	v_cmp_gt_u32_e32 vcc, 4, v1
	s_and_saveexec_b64 s[4:5], vcc
	v_lshl_add_u32 v2, v1, 2, 0
	v_add_u32_e32 v2, 0x27ff0, v2
	v_mov_b32_e32 v3, 0
	ds_write_b32 v2, v3
	s_or_b64 exec, exec, s[4:5]
	s_waitcnt lgkmcnt(0)
	s_barrier
	s_getreg_b32 s3, hwreg(HW_REG_XCC_ID, 0, 4)
	s_and_b32 s3, s3, 15
	v_writelane_b32 v255, s3, 2
	v_cmp_eq_u32_e32 vcc, 0, v1
	s_and_saveexec_b64 s[4:5], vcc
	s_cbranch_execz .LBB0_7
	s_mov_b64 s[8:9], exec
	v_mbcnt_lo_u32_b32 v1, s8, 0
	v_mbcnt_hi_u32_b32 v1, s9, v1
	v_cmp_eq_u32_e32 vcc, 0, v1
	s_and_saveexec_b64 s[6:7], vcc
	s_cbranch_execz .LBB0_6
	v_readlane_b32 s3, v255, 2
	s_lshl_b32 s3, s3, 8
	s_add_u32 s10, s76, s3
	s_addc_u32 s11, s77, 0
	s_bcnt1_i32_b64 s3, s[8:9]
	v_mov_b32_e32 v2, 0x1ebb8000
	v_mov_b32_e32 v3, s3
	global_atomic_add v2, v2, v3, s[10:11] offset:1024 sc0

.LBB0_524:
	s_or_b64 exec, exec, s[10:11]
	s_cmpk_eq_i32 s33, 0x100
	s_cselect_b64 s[84:85], -1, 0
	s_cmpk_lg_i32 s33, 0x100
	v_lshlrev_b32_e32 v2, 4, v137
	s_cselect_b64 s[4:5], -1, 0
	v_and_b32_e32 v104, 15, v137
	v_and_b32_e32 v93, 0x70, v2
	v_lshrrev_b32_e32 v2, 4, v119
	v_writelane_b32 v255, s4, 7
	v_lshrrev_b32_e32 v105, 6, v137
	v_lshlrev_b32_e32 v99, 3, v2
	v_lshlrev_b32_e32 v106, 2, v2
	v_mul_u32_u24_e32 v2, 0x110, v104
	v_and_b32_e32 v3, 48, v119
	v_writelane_b32 v255, s5, 8
	s_movk_i32 s3, 0x200
	v_lshrrev_b32_e32 v94, 3, v137
	v_lshlrev_b32_e32 v71, 4, v105
	s_movk_i32 s4, 0x1ff
	v_add3_u32 v100, 0, v2, v3
	s_cmpk_lt_i32 s2, 0x200
	v_mov_b32_e32 v65, 0
	s_mov_b32 s89, 0
	v_lshl_add_u32 v91, v93, 1, 0
	v_mul_u32_u24_e32 v92, 0x110, v94
	v_add_u32_e32 v95, 64, v94
	v_cmp_lt_u32_e64 s[4:5], s4, v137
	v_cmp_gt_u32_e64 s[6:7], s3, v137
	v_or_b32_e32 v96, 0x80, v94
	v_lshl_add_u32 v90, v119, 1, 0
	v_or_b32_e32 v97, 64, v119
	v_or_b32_e32 v98, 0x80, v119
	v_lshrrev_b32_e32 v110, 7, v137
	v_or_b32_e32 v108, 32, v104
	v_add_u32_e32 v101, 0x2200, v100
	v_or_b32_e32 v109, 64, v104
	v_add_u32_e32 v102, 0x4400, v100
	v_or_b32_e32 v107, 0x60, v104
	v_add_u32_e32 v103, 0x6600, v100
	v_lshlrev_b32_e32 v60, 1, v71
	v_lshlrev_b32_e32 v62, 1, v93
	s_barrier
	v_readlane_b32 s3, v255, 41
	s_cmp_eq_u32 s3, 0
	s_cbranch_scc1 .LBB0_552
	v_lshlrev_b32_e32 v3, 5, v105
	v_and_or_b32 v111, v3, 32, v104
	s_load_dwordx2 s[10:11], s[0:1], 0xd8
	s_load_dwordx2 s[12:13], s[0:1], 0x98
	v_or_b32_e32 v112, 16, v111
	v_sub_u32_e32 v3, v111, v106
	v_add_u32_e32 v113, 0x80, v3
	v_sub_u32_e32 v3, v112, v106
	v_or_b32_e32 v129, 0x80, v3
	v_mul_u32_u24_e32 v3, 0x190, v104
	v_lshlrev_b32_e32 v66, 1, v106
	v_add3_u32 v130, 0, v3, v66
	v_mul_u32_u24_e32 v3, 0x190, v108
	v_add3_u32 v131, 0, v3, v66
	v_mul_u32_u24_e32 v3, 0x190, v109
	s_waitcnt lgkmcnt(0)
	s_add_u32 s90, s10, 0xa5b8000
	v_add3_u32 v133, 0, v3, v66
	v_mul_u32_u24_e32 v3, 0x190, v107
	s_addc_u32 s91, s11, 0
	s_movk_i32 s3, 0xc0
	v_mul_u32_u24_e32 v2, 0x1900, v105
	v_add3_u32 v134, 0, v3, v66
	s_add_u32 s92, s10, 0x63b8000
	v_lshlrev_b32_e32 v64, 2, v93
	v_mbcnt_lo_u32_b32 v3, -1, 0
	v_cmp_gt_u32_e64 s[8:9], s3, v96
	v_or_b32_e32 v114, 2, v106
	v_or_b32_e32 v115, 3, v106
	v_or_b32_e32 v116, 32, v106
	v_or_b32_e32 v117, 33, v106
	v_or_b32_e32 v118, 34, v106
	v_or_b32_e32 v120, 35, v106
	v_or_b32_e32 v121, 64, v106
	v_or_b32_e32 v122, 0x41, v106
	v_or_b32_e32 v123, 0x42, v106
	v_or_b32_e32 v124, 0x43, v106
	v_or_b32_e32 v125, 0x60, v106
	v_or_b32_e32 v126, 0x61, v106
	v_or_b32_e32 v127, 0x62, v106
	v_or_b32_e32 v128, 0x63, v106
	v_add_u32_e32 v132, 0xcc00, v130
	s_addc_u32 s93, s11, 0
	v_lshl_add_u64 v[68:69], s[12:13], 0, v[64:65]
	s_add_i32 s3, s2, 0xffffff80
	s_lshl_b32 s3, s3, 6
	s_movk_i32 s87, 0x2000
	s_movk_i32 s86, 0x2c00
	s_mov_b64 s[94:95], 0x2a00
	s_movk_i32 s74, 0x2000
	s_mov_b64 s[96:97], 0x2800
	v_mov_b32_e32 v70, 0x358637bd
	s_mov_b32 s75, 0x800000
	v_mov_b64_e32 v[72:73], s[90:91]
	v_mov_b32_e32 v61, v65
	v_mov_b32_e32 v63, v65
	v_mbcnt_hi_u32_b32 v135, -1, v3
	v_add_u32_e32 v136, v90, v2
	v_mov_b32_e32 v138, 0x42800000
	v_not_b32_e32 v140, 63
	v_mov_b32_e32 v141, 0xff800000
	s_add_i32 s80, s2, 0xffffff80
	s_branch .LBB0_527
.LBB0_526:
	s_or_b64 exec, exec, s[82:83]
	s_addk_i32 s80, 0x80
	s_add_i32 s3, s3, s87
	s_cmpk_gt_i32 s80, 0x1ff
	s_cbranch_scc1 .LBB0_552

.LBB0_552:
	v_readlane_b32 s8, v255, 41
	s_cmp_lg_u32 s8, 0
	s_cbranch_scc1 .Lswa_ret_p4
	v_readlane_b32 s8, v255, 7
	v_readlane_b32 s9, v255, 8
	s_and_b64 vcc, exec, s[8:9]
	v_readlane_b32 s8, v255, 5
	v_readlane_b32 s9, v255, 6
	s_cbranch_vccz .LBB0_603
	s_movk_i32 s3, 0x80
	s_cmpk_gt_i32 s2, 0xff
	v_cmp_gt_u32_e64 s[22:23], s3, v137
	s_cbranch_scc1 .LBB0_570
	v_lshlrev_b32_e32 v2, 2, v137
	v_lshrrev_b32_e32 v7, 5, v137
	v_and_b32_e32 v6, 0x7c, v2
	v_lshlrev_b32_e32 v3, 9, v7
	v_lshlrev_b32_e32 v16, 2, v6
	v_add3_u32 v68, 0, v3, v16
	v_and_b32_e32 v3, 0x7f, v137
	v_add_u32_e32 v5, -1, v7
	v_cmp_gt_u32_e64 s[16:17], 32, v137
	v_lshlrev_b32_e32 v8, 2, v3
	v_mbcnt_lo_u32_b32 v3, -1, 0
	v_cndmask_b32_e64 v67, v5, 0, s[16:17]
	v_mov_b32_e32 v5, 0x1800
	v_mbcnt_hi_u32_b32 v3, -1, v3
	v_cndmask_b32_e64 v22, 0, v5, s[16:17]
	v_and_b32_e32 v5, 64, v3
	v_add_u32_e32 v5, 64, v5
	v_xor_b32_e32 v12, 1, v3
	v_cmp_lt_i32_e32 vcc, v12, v5
	s_load_dwordx4 s[28:31], s[0:1], 0xd0
	s_load_dwordx2 s[38:39], s[0:1], 0x88
	v_cndmask_b32_e32 v12, v3, v12, vcc
	v_lshlrev_b32_e32 v72, 2, v12
	v_xor_b32_e32 v12, 2, v3
	v_cmp_lt_i32_e32 vcc, v12, v5
	s_load_dwordx2 s[36:37], s[0:1], 0x70
	s_load_dwordx4 s[24:27], s[0:1], 0x10
	v_cndmask_b32_e32 v12, v3, v12, vcc
	v_lshlrev_b32_e32 v73, 2, v12
	v_xor_b32_e32 v12, 4, v3
	v_cmp_lt_i32_e32 vcc, v12, v5
	s_waitcnt lgkmcnt(0)
	s_add_u32 s20, s30, 0xa5b8000
	s_addc_u32 s21, s31, 0
	v_cndmask_b32_e32 v12, v3, v12, vcc
	v_lshlrev_b32_e32 v74, 2, v12
	v_xor_b32_e32 v12, 8, v3
	v_cmp_lt_i32_e32 vcc, v12, v5
	s_movk_i32 s3, 0x19f
	v_mov_b32_e32 v9, 0
	v_cndmask_b32_e32 v12, v3, v12, vcc
	v_lshlrev_b32_e32 v75, 2, v12
	v_xor_b32_e32 v12, 16, v3
	s_add_u32 s34, s30, 0x62b0000
	v_cmp_lt_i32_e32 vcc, v12, v5
	v_cmp_lt_u32_e64 s[10:11], s3, v137
	s_movk_i32 s3, 0x5f
	s_addc_u32 s35, s31, 0
	v_cndmask_b32_e32 v3, v3, v12, vcc
	v_lshl_add_u64 v[12:13], s[26:27], 0, v[8:9]
	v_lshl_add_u64 v[14:15], s[28:29], 0, v[8:9]
	s_mov_b64 s[26:27], 0x889c000
	v_add_u32_e32 v2, -3, v7
	v_cmp_lt_u32_e64 s[12:13], s3, v137
	s_movk_i32 s3, 0xc00
	v_add_u32_e32 v4, -2, v7
	v_cmp_lt_u32_e64 s[14:15], 63, v137
	v_lshl_add_u64 v[14:15], v[14:15], 0, s[26:27]
	s_add_u32 s26, s30, 0x63b8000
	v_cndmask_b32_e64 v63, 0, v2, s[12:13]
	v_mul_u32_u24_e32 v2, 0xc00, v7
	v_cndmask_b32_e64 v66, 0, v4, s[14:15]
	v_mad_u32_u24 v4, v7, s3, s3
	s_addc_u32 s27, s31, 0
	v_cndmask_b32_e64 v2, v2, 0, s[12:13]
	v_cndmask_b32_e64 v4, v4, 0, s[14:15]
	v_add_u32_e32 v70, 0, v8
	v_mov_b32_e32 v17, v9
	s_add_u32 s28, s28, 0x877c000
	v_cmp_gt_u32_e64 s[8:9], 16, v137
	v_add_u32_e32 v61, -13, v7
	s_mov_b32 s19, 0
	v_lshlrev_b32_e32 v10, 12, v110
	v_mov_b32_e32 v11, v9
	v_lshl_add_u32 v69, v110, 7, 0
	v_lshlrev_b32_e32 v76, 2, v3
	v_lshl_add_u64 v[16:17], s[38:39], 0, v[16:17]
	s_addc_u32 s29, s29, 0
	v_add_u32_e32 v77, 0x4000, v70
	s_mov_b32 s3, 0x41a00000
	s_mov_b32 s42, 0x3f2aaaab
	v_mov_b32_e32 v78, 0x3ecc95a3
	s_mov_b32 s43, 0x3f317218
	s_mov_b32 s44, 0x7f800000
	s_mov_b32 s45, 0x33800000
	s_mov_b32 s46, 0x9000
	s_movk_i32 s47, 0x3000
	s_movk_i32 s48, 0x2c00
	v_lshlrev_b32_e32 v18, 2, v2
	v_lshlrev_b32_e32 v20, 2, v4
	v_lshlrev_b32_e32 v22, 2, v22
	s_movk_i32 s49, 0x6000
	s_mov_b32 s50, 0x800000
	s_movk_i32 s51, 0x1000
	v_mov_b32_e32 v79, 0x358637bd
	v_lshlrev_b32_e32 v24, 1, v6
	v_mov_b32_e32 v26, 0x3f317218
	v_mov_b32_e32 v80, 0x7f800000
	v_mov_b32_e32 v81, 0x7fc00000
	v_mov_b32_e32 v82, 0xff800000
	s_mov_b32 s30, s2
	s_branch .LBB0_556

.LBB0_657:
	s_cmp_lt_i32 s78, 5
	s_cselect_b64 s[24:25], -1, 0
	s_and_b64 s[4:5], s[24:25], s[4:5]
	v_bfe_u32 v2, v0, 4, 2
	s_andn2_b64 vcc, exec, s[4:5]
	v_lshlrev_b32_e32 v254, 2, v2
	s_cbranch_vccnz .LBB0_814
	s_cmpk_lt_u32 s2, 0x80
	s_cbranch_scc1 .Lp4_after_swa
	v_and_b32_e32 v137, 0x3ff, v0
	s_mov_b32 s3, 1
	v_and_b32_e32 v119, 63, v137
	v_writelane_b32 v255, s3, 41
	s_branch .LBB0_524
.Lswa_ret_p4:
	s_mov_b32 s3, 0
	s_nop 0
	v_writelane_b32 v255, s3, 41
	s_mov_b64 s[24:25], -1
.Lp4_after_swa:
	s_cmpk_lg_i32 s33, 0x100
	s_load_dwordx2 s[26:27], s[0:1], 0xd8
	s_cselect_b64 s[4:5], -1, 0
	s_cmpk_lt_u32 s2, 0x80
	s_cselect_b64 s[6:7], -1, 0
	s_or_b64 s[8:9], s[6:7], s[4:5]
	v_bfe_u32 v2, v0, 6, 4
	v_and_b32_e32 v159, 0x3ff, v0
	s_movk_i32 s3, 0x80
	v_lshlrev_b32_e32 v152, 4, v2
	v_bfe_u32 v2, v0, 4, 2
	s_cmpk_lt_i32 s2, 0x80
	v_cmp_gt_u32_e64 s[4:5], s3, v159
	v_lshlrev_b32_e32 v126, 4, v159
	v_lshlrev_b32_e32 v161, 3, v2
	s_cselect_b64 s[30:31], -1, 0
	s_mov_b64 s[6:7], -1
	s_and_b64 vcc, exec, s[8:9]
	s_cbranch_vccz .LBB0_691
	s_andn2_b64 vcc, exec, s[30:31]
	s_cbranch_vccnz .LBB0_690
	v_lshlrev_b32_e32 v2, 4, v1
	s_waitcnt lgkmcnt(0)
	s_add_u32 s3, s26, 0x15b38000
	v_add_u32_e32 v155, 0, v2
	v_bfe_u32 v2, v0, 6, 4
	v_and_b32_e32 v6, 15, v0
	s_addc_u32 s23, s27, 0
	v_lshlrev_b32_e32 v2, 11, v2
	v_lshlrev_b32_e32 v3, 7, v6
	s_add_i32 s8, 0, 0x1d000
	v_add3_u32 v4, 0, v2, v3
	v_add3_u32 v3, s8, v2, v3
	v_bfe_u32 v2, v0, 4, 2
	v_mov_b32_e32 v131, 0
	s_movk_i32 s6, 0x100
	v_add_u32_e32 v153, 0, v126
	v_lshlrev_b32_e32 v2, 9, v2
	v_mul_u32_u24_e32 v128, 0x12100, v1
	v_mov_b32_e32 v129, v131
	v_cmp_gt_u32_e64 s[6:7], s6, v159
	v_mov_b32_e32 v127, v131
	v_add_u32_e32 v154, 0xf000, v153
	v_add_u32_e32 v156, 0xf000, v155
	v_or_b32_e32 v132, 0x4000, v126
	v_mov_b32_e32 v133, v131
	v_or_b32_e32 v134, 0x8000, v126
	v_mov_b32_e32 v135, v131
	v_or_b32_e32 v136, 0xc000, v126
	v_mov_b32_e32 v137, v131
	s_lshl_b32 s28, s2, 2
	s_lshl_b32 s29, s33, 2
	s_mov_b32 s34, 0x12000
	s_movk_i32 s35, 0x2000
	s_mov_b32 s36, 0x63b9000
	s_mov_b32 s37, 0x63bb000
	s_mov_b32 s38, 0x63c9000
	s_mov_b32 s39, 0x63cb000
	s_mov_b32 s40, 0x63d9000
	s_mov_b32 s41, 0x63db000
	s_mov_b32 s42, 0x63e8000
	s_mov_b32 s43, 0x63f9000
	s_mov_b32 s44, 0x63fb000
	s_mov_b32 s45, 0x6409000
	s_mov_b32 s46, 0x640b000
	s_mov_b32 s47, 0x6419000
	s_mov_b32 s48, 0x641b000
	s_mov_b32 s49, 0x6429000
	s_mov_b32 s50, 0x642b000
	s_mov_b64 s[8:9], 0x24200
	s_mov_b64 s[10:11], 0x80000
	v_lshlrev_b32_e32 v130, 2, v6
	v_lshlrev_b32_e32 v138, 2, v2
	s_mov_b64 s[12:13], 0x8424000
	s_mov_b32 s51, 0x8424000
	s_mov_b32 s52, 0x8426000
	s_mov_b32 s53, 0x8428000
	s_mov_b32 s54, 0x842a000
	s_mov_b32 s55, 0x842c000
	s_mov_b32 s56, 0x842e000
	v_add_u32_e32 v157, v4, v161
	v_add_u32_e32 v158, v3, v161
	s_mov_b32 s57, s2
	v_mov_b32_e32 v160, v252
	s_branch .LBB0_662
